# P1 U (bf16 activation) stores default cache policy instead of nt, on top of attention DMA spread
# speedup vs baseline: 1.0091x; 1.0046x over previous
; __device__ __forceinline__ unsigned cvt_pk_bf16(float lo, float hi) { const f32x2_t v = {lo, hi}; const bf16x2_t b = __builtin_convertvector(v, bf16x2_t); return __builtin_bit_cast(unsigned, b); }
;     __device__ __forceinline__ void operator()(f32x4 (&acc)[2][2][4][2], const Unit& u, int wr, int wc, int fr, int fq) const {
;     ...
;                 bf16_t* rowp = U + (size_t)r * LDU + g64 * 64 + 8 * fq;
; #pragma unroll
;                 for (int bj = 0; bj < 2; ++bj) {
;                     f32x4 v0 = v[bj][0], v1 = v[bj][1]; if (is_q) { v0 = v0 * post; v1 = v1 * post; }
;                     u32x4 w; w.x = cvt_pk_bf16(v0[0], v0[1]); w.y = cvt_pk_bf16(v0[2], v0[3]); w.z = cvt_pk_bf16(v1[0], v1[1]); w.w = cvt_pk_bf16(v1[2], v1[3]);
;                     __builtin_nontemporal_store(w, (u32x4*)(rowp + 32 * bj));
;                 }
.LBB0_165:
	v_mov_b64_e32 v[130:131], s[82:83]
	s_ashr_i32 s37, s36, 31
	v_mad_i64_i32 v[130:131], s[0:1], v132, s92, v[130:131]
	v_cndmask_b32_e64 v186, 1.0, v197, s[6:7]
	v_lshl_add_u64 v[130:131], s[36:37], 1, v[130:131]
	v_lshl_add_u64 v[134:135], v[130:131], 0, v[172:173]
	v_pk_mul_f32 v[130:131], v[186:187], v[146:147] op_sel_hi:[0,1]
	v_pk_mul_f32 v[132:133], v[186:187], v[148:149] op_sel_hi:[0,1]
	v_pk_mul_f32 v[136:137], v[186:187], v[150:151] op_sel_hi:[0,1]
	v_pk_mul_f32 v[138:139], v[186:187], v[152:153] op_sel_hi:[0,1]
	v_cndmask_b32_e64 v133, v149, v133, s[6:7]
	v_cndmask_b32_e64 v132, v148, v132, s[6:7]
	v_cndmask_b32_e64 v131, v147, v131, s[6:7]
	v_cndmask_b32_e64 v130, v146, v130, s[6:7]
	v_cndmask_b32_e64 v139, v153, v139, s[6:7]
	v_cndmask_b32_e64 v138, v152, v138, s[6:7]
	v_cndmask_b32_e64 v137, v151, v137, s[6:7]
	v_cndmask_b32_e64 v136, v150, v136, s[6:7]
	v_cvt_pk_bf16_f32 v130, v130, v131
	v_cvt_pk_bf16_f32 v131, v132, v133
	v_cvt_pk_bf16_f32 v132, v136, v137
	v_cvt_pk_bf16_f32 v133, v138, v139
	global_store_dwordx4 v[134:135], v[130:133], off
	v_pk_mul_f32 v[136:137], v[186:187], v[158:159] op_sel_hi:[0,1]
	v_pk_mul_f32 v[138:139], v[186:187], v[160:161] op_sel_hi:[0,1]
	v_pk_mul_f32 v[130:131], v[186:187], v[154:155] op_sel_hi:[0,1]
	v_pk_mul_f32 v[132:133], v[186:187], v[156:157] op_sel_hi:[0,1]
	v_cndmask_b32_e64 v133, v157, v133, s[6:7]
	v_cndmask_b32_e64 v132, v156, v132, s[6:7]
	v_cndmask_b32_e64 v131, v155, v131, s[6:7]
	v_cndmask_b32_e64 v130, v154, v130, s[6:7]
	v_cndmask_b32_e64 v139, v161, v139, s[6:7]
	v_cndmask_b32_e64 v138, v160, v138, s[6:7]
	v_cndmask_b32_e64 v137, v159, v137, s[6:7]
	v_cndmask_b32_e64 v136, v158, v136, s[6:7]
	v_cvt_pk_bf16_f32 v130, v130, v131
	v_cvt_pk_bf16_f32 v131, v132, v133
	v_cvt_pk_bf16_f32 v132, v136, v137
	v_cvt_pk_bf16_f32 v133, v138, v139
	global_store_dwordx4 v[134:135], v[130:133], off offset:64
	s_andn2_b64 vcc, exec, s[86:87]
	s_mov_b64 s[0:1], -1
	v_cndmask_b32_e64 v130, 0, 1, s[86:87]
	v_cmp_ne_u32_e64 s[12:13], 1, v130
	s_cbranch_vccnz .LBB0_183
	s_cmp_lt_i32 s15, 8
	s_cbranch_scc1 .LBB0_174
	s_cmp_gt_i32 s15, 9
	s_cselect_b64 s[10:11], -1, 0
	s_cbranch_execz .LBB0_175
	s_branch .LBB0_176

; __device__ __forceinline__ unsigned cvt_pk_bf16(float lo, float hi) { const f32x2_t v = {lo, hi}; const bf16x2_t b = __builtin_convertvector(v, bf16x2_t); return __builtin_bit_cast(unsigned, b); }
;     __device__ __forceinline__ void operator()(f32x4 (&acc)[2][2][4][2], const Unit& u, int wr, int wc, int fr, int fq) const {
;     ...
;                 bf16_t* rowp = U + (size_t)r * LDU + g64 * 64 + 8 * fq;
; #pragma unroll
;                 for (int bj = 0; bj < 2; ++bj) {
;                     f32x4 v0 = v[bj][0], v1 = v[bj][1]; if (is_q) { v0 = v0 * post; v1 = v1 * post; }
;                     u32x4 w; w.x = cvt_pk_bf16(v0[0], v0[1]); w.y = cvt_pk_bf16(v0[2], v0[3]); w.z = cvt_pk_bf16(v1[0], v1[1]); w.w = cvt_pk_bf16(v1[2], v1[3]);
;                     __builtin_nontemporal_store(w, (u32x4*)(rowp + 32 * bj));
;                 }
.LBB0_195:
	v_mov_b64_e32 v[114:115], s[82:83]
	v_mad_i64_i32 v[114:115], s[0:1], v116, s92, v[114:115]
	v_mov_b32_e32 v187, v186
	v_lshl_add_u64 v[114:115], s[36:37], 1, v[114:115]
	v_mov_b32_e32 v120, v186
	v_mov_b32_e32 v121, v186
	v_lshl_add_u64 v[118:119], v[114:115], 0, v[172:173]
	v_pk_mul_f32 v[114:115], v[120:121], v[132:133]
	v_pk_mul_f32 v[116:117], v[186:187], v[130:131]
	v_pk_mul_f32 v[122:123], v[120:121], v[136:137]
	v_pk_mul_f32 v[124:125], v[186:187], v[134:135]
	v_cndmask_b32_e64 v115, v133, v115, s[6:7]
	v_cndmask_b32_e64 v126, v132, v114, s[6:7]
	v_cndmask_b32_e64 v114, v131, v117, s[6:7]
	v_cndmask_b32_e64 v116, v130, v116, s[6:7]
	v_cndmask_b32_e64 v117, v137, v123, s[6:7]
	v_cndmask_b32_e64 v122, v136, v122, s[6:7]
	v_cndmask_b32_e64 v123, v135, v125, s[6:7]
	v_cndmask_b32_e64 v124, v134, v124, s[6:7]
	v_cvt_pk_bf16_f32 v114, v116, v114
	v_cvt_pk_bf16_f32 v115, v126, v115
	v_cvt_pk_bf16_f32 v116, v124, v123
	v_cvt_pk_bf16_f32 v117, v122, v117
	global_store_dwordx4 v[118:119], v[114:117], off
	v_pk_mul_f32 v[122:123], v[186:187], v[142:143]
	s_and_b64 vcc, exec, s[12:13]
	v_pk_mul_f32 v[114:115], v[120:121], v[140:141]
	v_pk_mul_f32 v[116:117], v[186:187], v[138:139]
	v_pk_mul_f32 v[120:121], v[120:121], v[144:145]
	v_cndmask_b32_e64 v115, v141, v115, s[6:7]
	v_cndmask_b32_e64 v124, v140, v114, s[6:7]
	v_cndmask_b32_e64 v114, v139, v117, s[6:7]
	v_cndmask_b32_e64 v116, v138, v116, s[6:7]
	v_cndmask_b32_e64 v117, v145, v121, s[6:7]
	v_cndmask_b32_e64 v120, v144, v120, s[6:7]
	v_cndmask_b32_e64 v121, v143, v123, s[6:7]
	v_cndmask_b32_e64 v122, v142, v122, s[6:7]
	v_cvt_pk_bf16_f32 v114, v116, v114
	v_cvt_pk_bf16_f32 v115, v124, v115
	v_cvt_pk_bf16_f32 v116, v122, v121
	v_cvt_pk_bf16_f32 v117, v120, v117
	s_mov_b64 s[0:1], -1
	global_store_dwordx4 v[118:119], v[114:117], off offset:64
	s_cbranch_vccnz .LBB0_198
	s_cmp_lt_i32 s15, 8
	s_cbranch_scc1 .LBB0_206
	s_cmp_gt_i32 s15, 9
	s_cselect_b64 s[86:87], -1, 0
	s_cbranch_execz .LBB0_207
	s_branch .LBB0_208

; __device__ __forceinline__ unsigned cvt_pk_bf16(float lo, float hi) { const f32x2_t v = {lo, hi}; const bf16x2_t b = __builtin_convertvector(v, bf16x2_t); return __builtin_bit_cast(unsigned, b); }
;     __device__ __forceinline__ void operator()(f32x4 (&acc)[2][2][4][2], const Unit& u, int wr, int wc, int fr, int fq) const {
;     ...
;                 bf16_t* rowp = U + (size_t)r * LDU + g64 * 64 + 8 * fq;
; #pragma unroll
;                 for (int bj = 0; bj < 2; ++bj) {
;                     f32x4 v0 = v[bj][0], v1 = v[bj][1]; if (is_q) { v0 = v0 * post; v1 = v1 * post; }
;                     u32x4 w; w.x = cvt_pk_bf16(v0[0], v0[1]); w.y = cvt_pk_bf16(v0[2], v0[3]); w.z = cvt_pk_bf16(v1[0], v1[1]); w.w = cvt_pk_bf16(v1[2], v1[3]);
;                     __builtin_nontemporal_store(w, (u32x4*)(rowp + 32 * bj));
;                 }
.LBB0_225:
	v_mov_b64_e32 v[98:99], s[82:83]
	v_mad_i64_i32 v[98:99], s[0:1], v100, s92, v[98:99]
	v_lshl_add_u64 v[98:99], s[36:37], 1, v[98:99]
	v_mov_b32_e32 v104, v186
	v_mov_b32_e32 v105, v186
	v_lshl_add_u64 v[102:103], v[98:99], 0, v[172:173]
	v_pk_mul_f32 v[98:99], v[104:105], v[116:117]
	v_pk_mul_f32 v[100:101], v[186:187], v[114:115]
	v_pk_mul_f32 v[106:107], v[104:105], v[120:121]
	v_pk_mul_f32 v[108:109], v[186:187], v[118:119]
	v_cndmask_b32_e64 v99, v117, v99, s[6:7]
	v_cndmask_b32_e64 v110, v116, v98, s[6:7]
	v_cndmask_b32_e64 v98, v115, v101, s[6:7]
	v_cndmask_b32_e64 v100, v114, v100, s[6:7]
	v_cndmask_b32_e64 v101, v121, v107, s[6:7]
	v_cndmask_b32_e64 v106, v120, v106, s[6:7]
	v_cndmask_b32_e64 v107, v119, v109, s[6:7]
	v_cndmask_b32_e64 v108, v118, v108, s[6:7]
	v_cvt_pk_bf16_f32 v98, v100, v98
	v_cvt_pk_bf16_f32 v99, v110, v99
	v_cvt_pk_bf16_f32 v100, v108, v107
	v_cvt_pk_bf16_f32 v101, v106, v101
	global_store_dwordx4 v[102:103], v[98:101], off
	v_pk_mul_f32 v[106:107], v[186:187], v[126:127]
	s_and_b64 vcc, exec, s[12:13]
	v_pk_mul_f32 v[98:99], v[104:105], v[124:125]
	v_pk_mul_f32 v[100:101], v[186:187], v[122:123]
	v_pk_mul_f32 v[104:105], v[104:105], v[128:129]
	v_cndmask_b32_e64 v99, v125, v99, s[6:7]
	v_cndmask_b32_e64 v108, v124, v98, s[6:7]
	v_cndmask_b32_e64 v98, v123, v101, s[6:7]
	v_cndmask_b32_e64 v100, v122, v100, s[6:7]
	v_cndmask_b32_e64 v101, v129, v105, s[6:7]
	v_cndmask_b32_e64 v104, v128, v104, s[6:7]
	v_cndmask_b32_e64 v105, v127, v107, s[6:7]
	v_cndmask_b32_e64 v106, v126, v106, s[6:7]
	v_cvt_pk_bf16_f32 v98, v100, v98
	v_cvt_pk_bf16_f32 v99, v108, v99
	v_cvt_pk_bf16_f32 v100, v106, v105
	v_cvt_pk_bf16_f32 v101, v104, v101
	s_mov_b64 s[0:1], -1
	global_store_dwordx4 v[102:103], v[98:101], off offset:64
	s_cbranch_vccnz .LBB0_228
	s_cmp_lt_i32 s15, 8
	s_cbranch_scc1 .LBB0_236
	s_cmp_gt_i32 s15, 9
	s_cselect_b64 s[86:87], -1, 0
	s_cbranch_execz .LBB0_237
	s_branch .LBB0_238

; __device__ __forceinline__ unsigned cvt_pk_bf16(float lo, float hi) { const f32x2_t v = {lo, hi}; const bf16x2_t b = __builtin_convertvector(v, bf16x2_t); return __builtin_bit_cast(unsigned, b); }
;     __device__ __forceinline__ void operator()(f32x4 (&acc)[2][2][4][2], const Unit& u, int wr, int wc, int fr, int fq) const {
;     ...
;                 bf16_t* rowp = U + (size_t)r * LDU + g64 * 64 + 8 * fq;
; #pragma unroll
;                 for (int bj = 0; bj < 2; ++bj) {
;                     f32x4 v0 = v[bj][0], v1 = v[bj][1]; if (is_q) { v0 = v0 * post; v1 = v1 * post; }
;                     u32x4 w; w.x = cvt_pk_bf16(v0[0], v0[1]); w.y = cvt_pk_bf16(v0[2], v0[3]); w.z = cvt_pk_bf16(v1[0], v1[1]); w.w = cvt_pk_bf16(v1[2], v1[3]);
;                     __builtin_nontemporal_store(w, (u32x4*)(rowp + 32 * bj));
;                 }
.LBB0_255:
	v_mov_b64_e32 v[82:83], s[82:83]
	v_mad_i64_i32 v[82:83], s[0:1], v84, s92, v[82:83]
	v_lshl_add_u64 v[82:83], s[36:37], 1, v[82:83]
	v_mov_b32_e32 v88, v186
	v_mov_b32_e32 v89, v186
	v_lshl_add_u64 v[86:87], v[82:83], 0, v[172:173]
	v_pk_mul_f32 v[82:83], v[88:89], v[100:101]
	v_pk_mul_f32 v[84:85], v[186:187], v[98:99]
	v_pk_mul_f32 v[90:91], v[88:89], v[104:105]
	v_pk_mul_f32 v[92:93], v[186:187], v[102:103]
	v_cndmask_b32_e64 v83, v101, v83, s[6:7]
	v_cndmask_b32_e64 v94, v100, v82, s[6:7]
	v_cndmask_b32_e64 v82, v99, v85, s[6:7]
	v_cndmask_b32_e64 v84, v98, v84, s[6:7]
	v_cndmask_b32_e64 v85, v105, v91, s[6:7]
	v_cndmask_b32_e64 v90, v104, v90, s[6:7]
	v_cndmask_b32_e64 v91, v103, v93, s[6:7]
	v_cndmask_b32_e64 v92, v102, v92, s[6:7]
	v_cvt_pk_bf16_f32 v82, v84, v82
	v_cvt_pk_bf16_f32 v83, v94, v83
	v_cvt_pk_bf16_f32 v84, v92, v91
	v_cvt_pk_bf16_f32 v85, v90, v85
	global_store_dwordx4 v[86:87], v[82:85], off
	v_pk_mul_f32 v[90:91], v[186:187], v[110:111]
	s_and_b64 vcc, exec, s[12:13]
	v_pk_mul_f32 v[82:83], v[88:89], v[108:109]
	v_pk_mul_f32 v[84:85], v[186:187], v[106:107]
	v_pk_mul_f32 v[88:89], v[88:89], v[112:113]
	v_cndmask_b32_e64 v83, v109, v83, s[6:7]
	v_cndmask_b32_e64 v92, v108, v82, s[6:7]
	v_cndmask_b32_e64 v82, v107, v85, s[6:7]
	v_cndmask_b32_e64 v84, v106, v84, s[6:7]
	v_cndmask_b32_e64 v85, v113, v89, s[6:7]
	v_cndmask_b32_e64 v88, v112, v88, s[6:7]
	v_cndmask_b32_e64 v89, v111, v91, s[6:7]
	v_cndmask_b32_e64 v90, v110, v90, s[6:7]
	v_cvt_pk_bf16_f32 v82, v84, v82
	v_cvt_pk_bf16_f32 v83, v92, v83
	v_cvt_pk_bf16_f32 v84, v90, v89
	v_cvt_pk_bf16_f32 v85, v88, v85
	s_mov_b64 s[0:1], -1
	global_store_dwordx4 v[86:87], v[82:85], off offset:64
	s_cbranch_vccnz .LBB0_273
	s_cmp_lt_i32 s15, 8
	s_cbranch_scc1 .LBB0_264
	s_cmp_gt_i32 s15, 9
	s_cselect_b64 s[86:87], -1, 0
	s_cbranch_execz .LBB0_265
	s_branch .LBB0_266

; __device__ __forceinline__ unsigned cvt_pk_bf16(float lo, float hi) { const f32x2_t v = {lo, hi}; const bf16x2_t b = __builtin_convertvector(v, bf16x2_t); return __builtin_bit_cast(unsigned, b); }
;     __device__ __forceinline__ void operator()(f32x4 (&acc)[2][2][4][2], const Unit& u, int wr, int wc, int fr, int fq) const {
;     ...
;                 bf16_t* rowp = U + (size_t)r * LDU + g64 * 64 + 8 * fq;
; #pragma unroll
;                 for (int bj = 0; bj < 2; ++bj) {
;                     f32x4 v0 = v[bj][0], v1 = v[bj][1]; if (is_q) { v0 = v0 * post; v1 = v1 * post; }
;                     u32x4 w; w.x = cvt_pk_bf16(v0[0], v0[1]); w.y = cvt_pk_bf16(v0[2], v0[3]); w.z = cvt_pk_bf16(v1[0], v1[1]); w.w = cvt_pk_bf16(v1[2], v1[3]);
;                     __builtin_nontemporal_store(w, (u32x4*)(rowp + 32 * bj));
;                 }
.LBB0_285:
	v_mov_b64_e32 v[66:67], s[82:83]
	v_mad_i64_i32 v[66:67], s[0:1], v68, s92, v[66:67]
	v_lshl_add_u64 v[66:67], s[36:37], 1, v[66:67]
	v_mov_b32_e32 v72, v186
	v_mov_b32_e32 v73, v186
	v_lshl_add_u64 v[70:71], v[66:67], 0, v[172:173]
	v_pk_mul_f32 v[66:67], v[72:73], v[84:85]
	v_pk_mul_f32 v[68:69], v[186:187], v[82:83]
	v_pk_mul_f32 v[74:75], v[72:73], v[88:89]
	v_pk_mul_f32 v[76:77], v[186:187], v[86:87]
	v_cndmask_b32_e64 v67, v85, v67, s[6:7]
	v_cndmask_b32_e64 v78, v84, v66, s[6:7]
	v_cndmask_b32_e64 v66, v83, v69, s[6:7]
	v_cndmask_b32_e64 v68, v82, v68, s[6:7]
	v_cndmask_b32_e64 v69, v89, v75, s[6:7]
	v_cndmask_b32_e64 v74, v88, v74, s[6:7]
	v_cndmask_b32_e64 v75, v87, v77, s[6:7]
	v_cndmask_b32_e64 v76, v86, v76, s[6:7]
	v_cvt_pk_bf16_f32 v66, v68, v66
	v_cvt_pk_bf16_f32 v67, v78, v67
	v_cvt_pk_bf16_f32 v68, v76, v75
	v_cvt_pk_bf16_f32 v69, v74, v69
	global_store_dwordx4 v[70:71], v[66:69], off
	v_pk_mul_f32 v[74:75], v[186:187], v[94:95]
	s_and_b64 vcc, exec, s[12:13]
	v_pk_mul_f32 v[66:67], v[72:73], v[92:93]
	v_pk_mul_f32 v[68:69], v[186:187], v[90:91]
	v_pk_mul_f32 v[72:73], v[72:73], v[96:97]
	v_cndmask_b32_e64 v67, v93, v67, s[6:7]
	v_cndmask_b32_e64 v76, v92, v66, s[6:7]
	v_cndmask_b32_e64 v66, v91, v69, s[6:7]
	v_cndmask_b32_e64 v68, v90, v68, s[6:7]
	v_cndmask_b32_e64 v69, v97, v73, s[6:7]
	v_cndmask_b32_e64 v72, v96, v72, s[6:7]
	v_cndmask_b32_e64 v73, v95, v75, s[6:7]
	v_cndmask_b32_e64 v74, v94, v74, s[6:7]
	v_cvt_pk_bf16_f32 v66, v68, v66
	v_cvt_pk_bf16_f32 v67, v76, v67
	v_cvt_pk_bf16_f32 v68, v74, v73
	v_cvt_pk_bf16_f32 v69, v72, v69
	s_mov_b64 s[0:1], -1
	global_store_dwordx4 v[70:71], v[66:69], off offset:64
	s_cbranch_vccnz .LBB0_288
	s_cmp_lt_i32 s15, 8
	s_cbranch_scc1 .LBB0_296
	s_cmp_gt_i32 s15, 9
	s_cselect_b64 s[86:87], -1, 0
	s_cbranch_execz .LBB0_297
	s_branch .LBB0_298

; __device__ __forceinline__ unsigned cvt_pk_bf16(float lo, float hi) { const f32x2_t v = {lo, hi}; const bf16x2_t b = __builtin_convertvector(v, bf16x2_t); return __builtin_bit_cast(unsigned, b); }
;     __device__ __forceinline__ void operator()(f32x4 (&acc)[2][2][4][2], const Unit& u, int wr, int wc, int fr, int fq) const {
;     ...
;                 bf16_t* rowp = U + (size_t)r * LDU + g64 * 64 + 8 * fq;
; #pragma unroll
;                 for (int bj = 0; bj < 2; ++bj) {
;                     f32x4 v0 = v[bj][0], v1 = v[bj][1]; if (is_q) { v0 = v0 * post; v1 = v1 * post; }
;                     u32x4 w; w.x = cvt_pk_bf16(v0[0], v0[1]); w.y = cvt_pk_bf16(v0[2], v0[3]); w.z = cvt_pk_bf16(v1[0], v1[1]); w.w = cvt_pk_bf16(v1[2], v1[3]);
;                     __builtin_nontemporal_store(w, (u32x4*)(rowp + 32 * bj));
;                 }
.LBB0_315:
	v_mov_b64_e32 v[50:51], s[82:83]
	v_mad_i64_i32 v[50:51], s[0:1], v52, s92, v[50:51]
	v_lshl_add_u64 v[50:51], s[36:37], 1, v[50:51]
	v_mov_b32_e32 v56, v186
	v_mov_b32_e32 v57, v186
	v_lshl_add_u64 v[54:55], v[50:51], 0, v[172:173]
	v_pk_mul_f32 v[50:51], v[56:57], v[68:69]
	v_pk_mul_f32 v[52:53], v[186:187], v[66:67]
	v_pk_mul_f32 v[58:59], v[56:57], v[72:73]
	v_pk_mul_f32 v[60:61], v[186:187], v[70:71]
	v_cndmask_b32_e64 v51, v69, v51, s[6:7]
	v_cndmask_b32_e64 v62, v68, v50, s[6:7]
	v_cndmask_b32_e64 v50, v67, v53, s[6:7]
	v_cndmask_b32_e64 v52, v66, v52, s[6:7]
	v_cndmask_b32_e64 v53, v73, v59, s[6:7]
	v_cndmask_b32_e64 v58, v72, v58, s[6:7]
	v_cndmask_b32_e64 v59, v71, v61, s[6:7]
	v_cndmask_b32_e64 v60, v70, v60, s[6:7]
	v_cvt_pk_bf16_f32 v50, v52, v50
	v_cvt_pk_bf16_f32 v51, v62, v51
	v_cvt_pk_bf16_f32 v52, v60, v59
	v_cvt_pk_bf16_f32 v53, v58, v53
	global_store_dwordx4 v[54:55], v[50:53], off
	v_pk_mul_f32 v[58:59], v[186:187], v[78:79]
	s_and_b64 vcc, exec, s[12:13]
	v_pk_mul_f32 v[50:51], v[56:57], v[76:77]
	v_pk_mul_f32 v[52:53], v[186:187], v[74:75]
	v_pk_mul_f32 v[56:57], v[56:57], v[80:81]
	v_cndmask_b32_e64 v51, v77, v51, s[6:7]
	v_cndmask_b32_e64 v60, v76, v50, s[6:7]
	v_cndmask_b32_e64 v50, v75, v53, s[6:7]
	v_cndmask_b32_e64 v52, v74, v52, s[6:7]
	v_cndmask_b32_e64 v53, v81, v57, s[6:7]
	v_cndmask_b32_e64 v56, v80, v56, s[6:7]
	v_cndmask_b32_e64 v57, v79, v59, s[6:7]
	v_cndmask_b32_e64 v58, v78, v58, s[6:7]
	v_cvt_pk_bf16_f32 v50, v52, v50
	v_cvt_pk_bf16_f32 v51, v60, v51
	v_cvt_pk_bf16_f32 v52, v58, v57
	v_cvt_pk_bf16_f32 v53, v56, v53
	s_mov_b64 s[0:1], -1
	global_store_dwordx4 v[54:55], v[50:53], off offset:64
	s_cbranch_vccnz .LBB0_318
	s_cmp_lt_i32 s15, 8
	s_cbranch_scc1 .LBB0_326
	s_cmp_gt_i32 s15, 9
	s_cselect_b64 s[86:87], -1, 0
	s_cbranch_execz .LBB0_327
	s_branch .LBB0_328

; __device__ __forceinline__ unsigned cvt_pk_bf16(float lo, float hi) { const f32x2_t v = {lo, hi}; const bf16x2_t b = __builtin_convertvector(v, bf16x2_t); return __builtin_bit_cast(unsigned, b); }
;     __device__ __forceinline__ void operator()(f32x4 (&acc)[2][2][4][2], const Unit& u, int wr, int wc, int fr, int fq) const {
;     ...
;                 bf16_t* rowp = U + (size_t)r * LDU + g64 * 64 + 8 * fq;
; #pragma unroll
;                 for (int bj = 0; bj < 2; ++bj) {
;                     f32x4 v0 = v[bj][0], v1 = v[bj][1]; if (is_q) { v0 = v0 * post; v1 = v1 * post; }
;                     u32x4 w; w.x = cvt_pk_bf16(v0[0], v0[1]); w.y = cvt_pk_bf16(v0[2], v0[3]); w.z = cvt_pk_bf16(v1[0], v1[1]); w.w = cvt_pk_bf16(v1[2], v1[3]);
;                     __builtin_nontemporal_store(w, (u32x4*)(rowp + 32 * bj));
;                 }
.LBB0_345:
	v_mov_b64_e32 v[18:19], s[82:83]
	v_mad_i64_i32 v[18:19], s[0:1], v20, s92, v[18:19]
	v_lshl_add_u64 v[18:19], s[36:37], 1, v[18:19]
	v_mov_b32_e32 v24, v186
	v_mov_b32_e32 v25, v186
	v_lshl_add_u64 v[22:23], v[18:19], 0, v[172:173]
	v_pk_mul_f32 v[18:19], v[24:25], v[52:53]
	v_pk_mul_f32 v[20:21], v[186:187], v[50:51]
	v_pk_mul_f32 v[34:35], v[24:25], v[56:57]
	v_pk_mul_f32 v[36:37], v[186:187], v[54:55]
	v_cndmask_b32_e64 v19, v53, v19, s[6:7]
	v_cndmask_b32_e64 v38, v52, v18, s[6:7]
	v_cndmask_b32_e64 v18, v51, v21, s[6:7]
	v_cndmask_b32_e64 v20, v50, v20, s[6:7]
	v_cndmask_b32_e64 v21, v57, v35, s[6:7]
	v_cndmask_b32_e64 v34, v56, v34, s[6:7]
	v_cndmask_b32_e64 v35, v55, v37, s[6:7]
	v_cndmask_b32_e64 v36, v54, v36, s[6:7]
	v_cvt_pk_bf16_f32 v18, v20, v18
	v_cvt_pk_bf16_f32 v19, v38, v19
	v_cvt_pk_bf16_f32 v20, v36, v35
	v_cvt_pk_bf16_f32 v21, v34, v21
	global_store_dwordx4 v[22:23], v[18:21], off
	v_pk_mul_f32 v[34:35], v[186:187], v[62:63]
	s_and_b64 vcc, exec, s[12:13]
	v_pk_mul_f32 v[18:19], v[24:25], v[60:61]
	v_pk_mul_f32 v[20:21], v[186:187], v[58:59]
	v_pk_mul_f32 v[24:25], v[24:25], v[64:65]
	v_cndmask_b32_e64 v19, v61, v19, s[6:7]
	v_cndmask_b32_e64 v36, v60, v18, s[6:7]
	v_cndmask_b32_e64 v18, v59, v21, s[6:7]
	v_cndmask_b32_e64 v20, v58, v20, s[6:7]
	v_cndmask_b32_e64 v21, v65, v25, s[6:7]
	v_cndmask_b32_e64 v24, v64, v24, s[6:7]
	v_cndmask_b32_e64 v25, v63, v35, s[6:7]
	v_cndmask_b32_e64 v34, v62, v34, s[6:7]
	v_cvt_pk_bf16_f32 v18, v20, v18
	v_cvt_pk_bf16_f32 v19, v36, v19
	v_cvt_pk_bf16_f32 v20, v34, v25
	v_cvt_pk_bf16_f32 v21, v24, v21
	s_mov_b64 s[0:1], -1
	global_store_dwordx4 v[22:23], v[18:21], off offset:64
	s_cbranch_vccnz .LBB0_348
	s_cmp_lt_i32 s15, 8
	s_cbranch_scc1 .LBB0_356
	s_cmp_gt_i32 s15, 9
	s_cselect_b64 s[12:13], -1, 0
	s_cbranch_execz .LBB0_357
	s_branch .LBB0_358

; __device__ __forceinline__ unsigned cvt_pk_bf16(float lo, float hi) { const f32x2_t v = {lo, hi}; const bf16x2_t b = __builtin_convertvector(v, bf16x2_t); return __builtin_bit_cast(unsigned, b); }
; #define PG8_BAR __builtin_amdgcn_s_barrier()
; template <class Epi, int AC0, int BC0, int NT0, int AC1, int BC1, int NT1>
; __device__ __forceinline__ void gemm_phase(LAS unsigned char* lds, const Gemm g, const StaticOrder& S, const Epi& E, int tid) {
;     ...
;         if (wr == 0) PG8_BAR;
;         E(acc, cur, wr, wc, fr, fq);
;         if (!has_next) break;
;         if (!(Epi::KEEP0 && cur.seg == 0)) {
; #pragma unroll
;             for (int a = 0; a < 2; ++a)
; #pragma unroll
;                 for (int b = 0; b < 2; ++b)
; #pragma unroll
;                     for (int m = 0; m < 4; ++m)
; #pragma unroll
;                         for (int n = 0; n < 2; ++n) acc[a][b][m][n] = (f32x4){0.f, 0.f, 0.f, 0.f};
;         }
;         cur = nxt; cA = nA; cB = nB; ++ui;
;         if (wr == 1) PG8_BAR;
;     __device__ __forceinline__ void operator()(f32x4 (&acc)[2][2][4][2], const Unit& u, int wr, int wc, int fr, int fq) const {
;     ...
;                 bf16_t* rowp = U + (size_t)r * LDU + g64 * 64 + 8 * fq;
; #pragma unroll
;                 for (int bj = 0; bj < 2; ++bj) {
;                     f32x4 v0 = v[bj][0], v1 = v[bj][1]; if (is_q) { v0 = v0 * post; v1 = v1 * post; }
;                     u32x4 w; w.x = cvt_pk_bf16(v0[0], v0[1]); w.y = cvt_pk_bf16(v0[2], v0[3]); w.z = cvt_pk_bf16(v1[0], v1[1]); w.w = cvt_pk_bf16(v1[2], v1[3]);
;                     __builtin_nontemporal_store(w, (u32x4*)(rowp + 32 * bj));
;                 }
.LBB0_375:
	v_mov_b64_e32 v[2:3], s[82:83]
	v_mad_i64_i32 v[2:3], s[0:1], v4, s92, v[2:3]
	v_lshl_add_u64 v[2:3], s[36:37], 1, v[2:3]
	v_mov_b32_e32 v8, v186
	v_mov_b32_e32 v9, v186
	v_lshl_add_u64 v[6:7], v[2:3], 0, v[172:173]
	v_pk_mul_f32 v[2:3], v[8:9], v[20:21]
	v_pk_mul_f32 v[4:5], v[186:187], v[18:19]
	v_pk_mul_f32 v[10:11], v[8:9], v[24:25]
	v_pk_mul_f32 v[12:13], v[186:187], v[22:23]
	v_cndmask_b32_e64 v3, v21, v3, s[6:7]
	v_cndmask_b32_e64 v14, v20, v2, s[6:7]
	v_cndmask_b32_e64 v2, v19, v5, s[6:7]
	v_cndmask_b32_e64 v4, v18, v4, s[6:7]
	v_cndmask_b32_e64 v5, v25, v11, s[6:7]
	v_cndmask_b32_e64 v10, v24, v10, s[6:7]
	v_cndmask_b32_e64 v11, v23, v13, s[6:7]
	v_cndmask_b32_e64 v12, v22, v12, s[6:7]
	v_cvt_pk_bf16_f32 v2, v4, v2
	v_cvt_pk_bf16_f32 v3, v14, v3
	v_cvt_pk_bf16_f32 v4, v12, v11
	v_cvt_pk_bf16_f32 v5, v10, v5
	global_store_dwordx4 v[6:7], v[2:5], off
	v_pk_mul_f32 v[10:11], v[186:187], v[38:39]
	s_andn2_b64 vcc, exec, s[4:5]
	v_pk_mul_f32 v[2:3], v[8:9], v[36:37]
	v_pk_mul_f32 v[4:5], v[186:187], v[34:35]
	v_pk_mul_f32 v[8:9], v[8:9], v[40:41]
	v_cndmask_b32_e64 v3, v37, v3, s[6:7]
	v_cndmask_b32_e64 v12, v36, v2, s[6:7]
	v_cndmask_b32_e64 v2, v35, v5, s[6:7]
	v_cndmask_b32_e64 v4, v34, v4, s[6:7]
	v_cndmask_b32_e64 v5, v41, v9, s[6:7]
	v_cndmask_b32_e64 v8, v40, v8, s[6:7]
	v_cndmask_b32_e64 v9, v39, v11, s[6:7]
	v_cndmask_b32_e64 v10, v38, v10, s[6:7]
	v_cvt_pk_bf16_f32 v2, v4, v2
	v_cvt_pk_bf16_f32 v3, v12, v3
	v_cvt_pk_bf16_f32 v4, v10, v9
	v_cvt_pk_bf16_f32 v5, v8, v5
	s_mov_b64 s[0:1], -1
	global_store_dwordx4 v[6:7], v[2:5], off offset:64
	s_cbranch_vccnz .LBB0_116
	v_readlane_b32 s0, v254, 15
	v_readlane_b32 s1, v254, 16
	s_andn2_b64 vcc, exec, s[0:1]
	s_cbranch_vccnz .LBB0_115
	s_barrier
	s_branch .LBB0_115
